# NSA top-16 selection: three LDS shuffle hops per round replaced by DPP max within the 8-lane group
# speedup vs baseline: 1.0215x; 1.0023x over previous
; DEV unsigned shxu(unsigned v, int m, int lane) { return (unsigned)__builtin_amdgcn_ds_bpermute((lane ^ m) << 2, (int)v); }
; DEV void attn_nsa_phase(LAS unsigned char* lds, unsigned char* ws, int tid0, int G, int c) {
;     ...
;             for (int round = 0; round < 16; ++round) {
;                 unsigned m = 0u;
; #pragma unroll
;                 for (int k = 0; k < 16; ++k) m = key[k] > m ? key[k] : m;
;                 { unsigned t = shxu(m, 1, lane); m = t > m ? t : m; t = shxu(m, 2, lane); m = t > m ? t : m; t = shxu(m, 4, lane); m = t > m ? t : m; }
;                 if (m != 0u) { const int s = 255 - (int)(m & 255u); const unsigned bit = 1u << (s & 31); const int sw = s >> 5;
;                     w0 |= sw == 0 ? bit : 0u; w1 |= sw == 1 ? bit : 0u; w2 |= sw == 2 ? bit : 0u; w3 |= sw == 3 ? bit : 0u;
; #pragma unroll
;                     for (int k = 0; k < 16; ++k) key[k] = key[k] == m ? 0u : key[k]; }
;             }
.LBB0_2749:
	v_max_u32_e32 v25, v7, v6
	v_max3_u32 v25, v9, v8, v25
	v_max3_u32 v25, v11, v10, v25
	v_max3_u32 v25, v13, v12, v25
	v_max3_u32 v25, v15, v14, v25
	v_max3_u32 v25, v17, v16, v25
	v_max3_u32 v25, v19, v18, v25
	v_max3_u32 v25, v21, v20, v25
	s_nop 1
	v_max_u32_dpp v25, v25, v25 quad_perm:[1,0,3,2] row_mask:0xf bank_mask:0xf bound_ctrl:1
	s_nop 1
	v_max_u32_dpp v25, v25, v25 quad_perm:[2,3,0,1] row_mask:0xf bank_mask:0xf bound_ctrl:1
	s_nop 1
	v_max_u32_dpp v25, v25, v25 row_half_mirror row_mask:0xf bank_mask:0xf bound_ctrl:1
	v_cmp_ne_u32_e64 s[0:1], 0, v25
	s_and_saveexec_b64 s[6:7], s[0:1]
	s_cbranch_execz .LBB0_2748
	v_not_b32_e32 v26, v25
	v_bitop3_b32 v27, v25, s67, v25 bitop3:0xc
	v_lshlrev_b32_e64 v28, v26, 1
	v_bfe_u32 v26, v26, 5, 3
	v_cmp_gt_u32_e64 s[0:1], 32, v27
	s_nop 1
	v_cndmask_b32_e64 v27, 0, v28, s[0:1]
	v_cmp_eq_u32_e64 s[0:1], 1, v26
	v_or_b32_e32 v2, v27, v2
	s_nop 0
	v_cndmask_b32_e64 v29, 0, v28, s[0:1]
	v_cmp_eq_u32_e64 s[0:1], 2, v26
	v_or_b32_e32 v3, v29, v3
	s_nop 0
	v_cndmask_b32_e64 v30, 0, v28, s[0:1]
	v_cmp_eq_u32_e64 s[0:1], 3, v26
	v_or_b32_e32 v4, v30, v4
	s_nop 0
	v_cndmask_b32_e64 v26, 0, v28, s[0:1]
	v_cmp_ne_u32_e64 s[0:1], v6, v25
	v_or_b32_e32 v5, v26, v5
	s_nop 0
	v_cndmask_b32_e64 v6, 0, v6, s[0:1]
	v_cmp_ne_u32_e64 s[0:1], v7, v25
	s_nop 1
	v_cndmask_b32_e64 v7, 0, v7, s[0:1]
	v_cmp_ne_u32_e64 s[0:1], v8, v25
	s_nop 1
	v_cndmask_b32_e64 v8, 0, v8, s[0:1]
	v_cmp_ne_u32_e64 s[0:1], v9, v25
	s_nop 1
	v_cndmask_b32_e64 v9, 0, v9, s[0:1]
	v_cmp_ne_u32_e64 s[0:1], v10, v25
	s_nop 1
	v_cndmask_b32_e64 v10, 0, v10, s[0:1]
	v_cmp_ne_u32_e64 s[0:1], v11, v25
	s_nop 1
	v_cndmask_b32_e64 v11, 0, v11, s[0:1]
	v_cmp_ne_u32_e64 s[0:1], v12, v25
	s_nop 1
	v_cndmask_b32_e64 v12, 0, v12, s[0:1]
	v_cmp_ne_u32_e64 s[0:1], v13, v25
	s_nop 1
	v_cndmask_b32_e64 v13, 0, v13, s[0:1]
	v_cmp_ne_u32_e64 s[0:1], v14, v25
	s_nop 1
	v_cndmask_b32_e64 v14, 0, v14, s[0:1]
	v_cmp_ne_u32_e64 s[0:1], v15, v25
	s_nop 1
	v_cndmask_b32_e64 v15, 0, v15, s[0:1]
	v_cmp_ne_u32_e64 s[0:1], v16, v25
	s_nop 1
	v_cndmask_b32_e64 v16, 0, v16, s[0:1]
	v_cmp_ne_u32_e64 s[0:1], v17, v25
	s_nop 1
	v_cndmask_b32_e64 v17, 0, v17, s[0:1]
	v_cmp_ne_u32_e64 s[0:1], v18, v25
	s_nop 1
	v_cndmask_b32_e64 v18, 0, v18, s[0:1]
	v_cmp_ne_u32_e64 s[0:1], v19, v25
	s_nop 1
	v_cndmask_b32_e64 v19, 0, v19, s[0:1]
	v_cmp_ne_u32_e64 s[0:1], v20, v25
	s_nop 1
	v_cndmask_b32_e64 v20, 0, v20, s[0:1]
	v_cmp_ne_u32_e64 s[0:1], v21, v25
	s_nop 1
	v_cndmask_b32_e64 v21, 0, v21, s[0:1]
	s_branch .LBB0_2748
